# convert-tile loop of layer-1 mixing tail: next tile's loads stay in flight across gather+stores; carry-in loads batched; memkv0 loads batched
# speedup vs baseline: 1.0321x; 1.0073x over previous
.LBB0_370:
	v_mov_b32_e32 v1, v181
	s_and_b32 s5, s0, 0x3e0
	v_readfirstlane_b32 s3, v1
	s_ashr_i32 s4, s3, 6
	v_bfi_b32 v2, 31, v1, s1
	v_ashrrev_i32_e32 v3, 31, v2
	s_lshl_b32 s6, s4, 8
	v_lshlrev_b64 v[2:3], 12, v[2:3]
	s_ashr_i32 s7, s6, 31
	v_and_or_b32 v30, v1, 31, s5
	s_waitcnt vmcnt(2)
	v_lshlrev_b32_e32 v4, 12, v30
	v_mov_b32_e32 v5, v0
	s_lshl_b64 s[6:7], s[6:7], 1
	v_lshl_add_u64 v[2:3], s[82:83], 0, v[2:3]
	v_lshrrev_b32_e32 v6, 1, v1
	v_lshl_add_u64 v[4:5], s[88:89], 0, v[4:5]
	v_lshl_add_u64 v[2:3], v[2:3], 0, s[6:7]
	v_and_b32_e32 v6, 16, v6
	v_mov_b32_e32 v7, v0
	v_lshl_add_u64 v[4:5], v[4:5], 0, s[6:7]
	v_lshl_add_u64 v[26:27], v[2:3], 0, v[6:7]
	v_lshl_add_u64 v[28:29], v[4:5], 0, v[6:7]
	global_load_dwordx4 v[2:5], v[26:27], off
	global_load_dwordx4 v[6:9], v[28:29], off
	global_load_dwordx4 v[18:21], v[26:27], off offset:32
	global_load_dwordx4 v[22:25], v[28:29], off offset:32
	global_load_dwordx4 v[58:61], v[26:27], off offset:64
	global_load_dwordx4 v[62:65], v[28:29], off offset:64
	global_load_dwordx4 v[66:69], v[26:27], off offset:96
	global_load_dwordx4 v[70:73], v[28:29], off offset:96
	global_load_dwordx4 v[74:77], v[26:27], off offset:128
	global_load_dwordx4 v[78:81], v[28:29], off offset:128
	global_load_dwordx4 v[82:85], v[26:27], off offset:160
	global_load_dwordx4 v[86:89], v[28:29], off offset:160
	global_load_dwordx4 v[90:93], v[26:27], off offset:192
	global_load_dwordx4 v[94:97], v[28:29], off offset:192
	global_load_dwordx4 v[98:101], v[26:27], off offset:224
	global_load_dwordx4 v[102:105], v[28:29], off offset:224
	global_load_dwordx4 v[106:109], v[26:27], off offset:256
	global_load_dwordx4 v[110:113], v[28:29], off offset:256
	global_load_dwordx4 v[114:117], v[26:27], off offset:288
	global_load_dwordx4 v[118:121], v[28:29], off offset:288
	global_load_dwordx4 v[122:125], v[26:27], off offset:320
	global_load_dwordx4 v[126:129], v[28:29], off offset:320
	global_load_dwordx4 v[222:225], v[26:27], off offset:352
	global_load_dwordx4 v[226:229], v[28:29], off offset:352
	global_load_dwordx4 v[230:233], v[26:27], off offset:384
	global_load_dwordx4 v[234:237], v[28:29], off offset:384
	global_load_dwordx4 v[238:241], v[26:27], off offset:416
	global_load_dwordx4 v[242:245], v[28:29], off offset:416
	global_load_dwordx4 v[140:143], v[26:27], off offset:448
	global_load_dwordx4 v[144:147], v[28:29], off offset:448
	global_load_dwordx4 v[148:151], v[26:27], off offset:480
	global_load_dwordx4 v[182:185], v[28:29], off offset:480
	s_lshl_b32 s4, s4, 12
	s_add_i32 s4, s4, 0
	s_and_b32 s3, s1, 0xffffffe0
	s_add_i32 s1, s1, s86
	s_waitcnt vmcnt(30)
	v_mfma_f32_32x32x16_bf16 v[2:17], v[2:5], v[6:9], 0
	s_waitcnt vmcnt(28)
	v_mfma_f32_32x32x16_bf16 v[2:17], v[18:21], v[22:25], v[2:17]
	s_waitcnt vmcnt(26)
	v_mfma_f32_32x32x16_bf16 v[2:17], v[58:61], v[62:65], v[2:17]
	s_waitcnt vmcnt(24)
	v_mfma_f32_32x32x16_bf16 v[2:17], v[66:69], v[70:73], v[2:17]
	s_waitcnt vmcnt(22)
	v_mfma_f32_32x32x16_bf16 v[2:17], v[74:77], v[78:81], v[2:17]
	s_waitcnt vmcnt(20)
	v_mfma_f32_32x32x16_bf16 v[2:17], v[82:85], v[86:89], v[2:17]
	s_waitcnt vmcnt(18)
	v_mfma_f32_32x32x16_bf16 v[2:17], v[90:93], v[94:97], v[2:17]
	s_waitcnt vmcnt(16)
	v_mfma_f32_32x32x16_bf16 v[2:17], v[98:101], v[102:105], v[2:17]
	s_waitcnt vmcnt(14)
	v_mfma_f32_32x32x16_bf16 v[2:17], v[106:109], v[110:113], v[2:17]
	s_waitcnt vmcnt(12)
	v_mfma_f32_32x32x16_bf16 v[2:17], v[114:117], v[118:121], v[2:17]
	s_waitcnt vmcnt(10)
	v_mfma_f32_32x32x16_bf16 v[2:17], v[122:125], v[126:129], v[2:17]
	s_waitcnt vmcnt(8)
	v_mfma_f32_32x32x16_bf16 v[2:17], v[222:225], v[226:229], v[2:17]
	s_waitcnt vmcnt(6)
	v_mfma_f32_32x32x16_bf16 v[2:17], v[230:233], v[234:237], v[2:17]
	s_waitcnt vmcnt(4)
	v_mfma_f32_32x32x16_bf16 v[2:17], v[238:241], v[242:245], v[2:17]
	s_waitcnt vmcnt(2)
	v_mfma_f32_32x32x16_bf16 v[2:17], v[140:143], v[144:147], v[2:17]
	s_waitcnt vmcnt(0)
	v_mfma_f32_32x32x16_bf16 v[2:17], v[148:151], v[182:185], v[2:17]
	v_lshlrev_b32_e32 v18, 2, v1
	v_and_b32_e32 v18, 0xfc, v18
	v_add_u32_e32 v19, s4, v18
	s_nop 8
	ds_write2st64_b32 v19, v2, v3 offset1:1
	ds_write2st64_b32 v19, v4, v5 offset0:2 offset1:3
	ds_write2st64_b32 v19, v6, v7 offset0:4 offset1:5
	ds_write2st64_b32 v19, v8, v9 offset0:6 offset1:7
	ds_write2st64_b32 v19, v10, v11 offset0:8 offset1:9
	ds_write2st64_b32 v19, v12, v13 offset0:10 offset1:11
	ds_write2st64_b32 v19, v14, v15 offset0:12 offset1:13
	ds_write2st64_b32 v19, v16, v17 offset0:14 offset1:15
	v_add_u32_e32 v8, 0, v18
	v_and_b32_e32 v4, 0x3fffffc0, v1
	v_lshl_add_u32 v6, v4, 2, v8
	s_waitcnt lgkmcnt(0)
	s_barrier
	ds_read2st64_b32 v[4:5], v6 offset1:16
	v_lshrrev_b32_e32 v2, 3, v1
	v_and_b32_e32 v2, 4, v2
	v_bfe_u32 v3, v1, 6, 2
	v_or3_b32 v9, v3, v2, s3
	s_waitcnt lgkmcnt(0)
	v_add_f32_e32 v4, 0, v4
	v_add_f32_e32 v7, v4, v5
	ds_read2st64_b32 v[4:5], v6 offset0:32 offset1:48
	v_lshlrev_b32_e32 v2, 1, v30
	v_mov_b32_e32 v3, v0
	v_lshl_add_u64 v[2:3], s[84:85], 0, v[2:3]
	s_waitcnt lgkmcnt(0)
	v_add_f32_e32 v4, v7, v4
	v_add_f32_e32 v7, v4, v5
	ds_read2st64_b32 v[4:5], v6 offset0:64 offset1:80
	s_waitcnt lgkmcnt(0)
	v_add_f32_e32 v4, v7, v4
	v_add_f32_e32 v7, v4, v5
	ds_read2st64_b32 v[4:5], v6 offset0:96 offset1:112
	s_waitcnt lgkmcnt(0)
	v_add_f32_e32 v4, v7, v4
	v_add_f32_e32 v10, v4, v5
	v_ashrrev_i32_e32 v4, 5, v1
	v_and_b32_e32 v4, -8, v4
	v_add_u32_e32 v4, v9, v4
	v_ashrrev_i32_e32 v5, 31, v4
	v_lshl_add_u64 v[6:7], v[4:5], 3, s[92:93]
	global_load_dwordx2 v[6:7], v[6:7], off
	v_lshlrev_b64 v[4:5], 13, v[4:5]
	v_lshl_add_u64 v[4:5], v[2:3], 0, v[4:5]
	v_add_u32_e32 v1, 0x200, v1
	s_waitcnt vmcnt(0)
	v_ffbh_u32_e32 v11, v7
	v_min_u32_e32 v11, 32, v11
	v_lshlrev_b64 v[6:7], v11, v[6:7]
	v_min_u32_e32 v6, 1, v6
	v_or_b32_e32 v6, v7, v6
	v_cvt_f32_u32_e32 v6, v6
	v_sub_u32_e32 v7, 32, v11
	v_ldexp_f32 v6, v6, v7
	v_fmamk_f32 v6, v6, 0x2e000000, v211
	v_cmp_gt_f32_e32 vcc, s20, v6
	v_mul_f32_e32 v7, 0x4b800000, v6
	s_nop 0
	v_cndmask_b32_e32 v6, v6, v7, vcc
	v_rsq_f32_e32 v6, v6
	s_nop 0
	v_mul_f32_e32 v7, 0x45800000, v6
	v_cndmask_b32_e32 v6, v6, v7, vcc
	v_mul_f32_e32 v6, v10, v6
	v_cvt_pk_bf16_f32 v6, v6, s0
	global_store_short v[4:5], v6, off
	v_and_b32_e32 v4, 0x3fffffc0, v1
	v_lshl_add_u32 v6, v4, 2, v8
	ds_read2st64_b32 v[4:5], v6 offset1:16
	v_ashrrev_i32_e32 v1, 5, v1
	v_and_b32_e32 v1, -8, v1
	s_waitcnt lgkmcnt(0)
	v_add_f32_e32 v4, 0, v4
	v_add_f32_e32 v7, v4, v5
	ds_read2st64_b32 v[4:5], v6 offset0:32 offset1:48
	s_waitcnt lgkmcnt(0)
	v_add_f32_e32 v4, v7, v4
	v_add_f32_e32 v7, v4, v5
	ds_read2st64_b32 v[4:5], v6 offset0:64 offset1:80
	s_waitcnt lgkmcnt(0)
	v_add_f32_e32 v4, v7, v4
	v_add_f32_e32 v7, v4, v5
	ds_read2st64_b32 v[4:5], v6 offset0:96 offset1:112
	s_waitcnt lgkmcnt(0)
	v_add_f32_e32 v4, v7, v4
	v_add_f32_e32 v8, v4, v5
	v_add_u32_e32 v4, v9, v1
	v_ashrrev_i32_e32 v5, 31, v4
	v_lshl_add_u64 v[6:7], v[4:5], 3, s[92:93]
	global_load_dwordx2 v[6:7], v[6:7], off
	v_lshlrev_b64 v[4:5], 13, v[4:5]
	v_lshl_add_u64 v[2:3], v[2:3], 0, v[4:5]
	s_waitcnt vmcnt(0)
	v_ffbh_u32_e32 v1, v7
	v_min_u32_e32 v1, 32, v1
	v_lshlrev_b64 v[6:7], v1, v[6:7]
	v_min_u32_e32 v6, 1, v6
	v_or_b32_e32 v6, v7, v6
	v_cvt_f32_u32_e32 v6, v6
	v_sub_u32_e32 v1, 32, v1
	v_ldexp_f32 v1, v6, v1
	v_fmamk_f32 v1, v1, 0x2e000000, v211
	v_cmp_gt_f32_e32 vcc, s20, v1
	v_mul_f32_e32 v6, 0x4b800000, v1
	s_nop 0
	v_cndmask_b32_e32 v1, v1, v6, vcc
	v_rsq_f32_e32 v1, v1
	s_nop 0
	v_mul_f32_e32 v6, 0x45800000, v1
	v_cndmask_b32_e32 v1, v1, v6, vcc
	v_mul_f32_e32 v1, v8, v1
	v_cvt_pk_bf16_f32 v1, v1, s0
	s_add_i32 s0, s0, s8
	s_cmpk_lt_i32 s1, 0x100
	global_store_short v[2:3], v1, off
	s_barrier
	s_cbranch_scc1 .LBB0_370

.LBB0_570:
	s_or_b64 exec, exec, s[8:9]
	s_lshr_b32 s0, s21, 1
	v_and_b32_e32 v13, 31, v6
	s_and_b32 s0, s0, 0x60
	v_readlane_b32 s9, v246, 0
	v_or_b32_e32 v5, s0, v13
	s_mul_i32 s0, s9, 24
	s_add_i32 s4, s4, s0
	s_lshl_b32 s4, s4, 15
	v_readlane_b32 s5, v249, 4
	s_add_u32 s0, s5, s4
	v_readlane_b32 s8, v249, 5
	s_addc_u32 s1, s8, 0
	v_lshlrev_b32_e32 v8, 8, v5
	v_mov_b32_e32 v9, v0
	s_add_i32 s4, s4, 0x60000
	v_bfe_u32 v12, v6, 5, 1
	v_lshl_add_u64 v[10:11], s[0:1], 0, v[8:9]
	s_add_u32 s0, s5, s4
	v_lshlrev_b32_e32 v36, 4, v12
	v_mov_b32_e32 v37, v0
	s_addc_u32 s1, s8, 0
	v_lshl_add_u64 v[10:11], v[10:11], 0, v[36:37]
	v_lshl_add_u64 v[8:9], s[0:1], 0, v[8:9]
	v_lshl_add_u64 v[8:9], v[8:9], 0, v[36:37]
	global_load_dwordx4 v[68:71], v[10:11], off
	global_load_dwordx4 v[72:75], v[10:11], off offset:32
	global_load_dwordx4 v[76:79], v[8:9], off
	global_load_dwordx4 v[80:83], v[8:9], off offset:32
	global_load_dwordx4 v[84:87], v[10:11], off offset:64
	global_load_dwordx4 v[88:91], v[10:11], off offset:96
	global_load_dwordx4 v[92:95], v[8:9], off offset:64
	global_load_dwordx4 v[96:99], v[8:9], off offset:96
	global_load_dwordx4 v[100:103], v[10:11], off offset:128
	global_load_dwordx4 v[104:107], v[10:11], off offset:160
	global_load_dwordx4 v[108:111], v[8:9], off offset:128
	global_load_dwordx4 v[112:115], v[8:9], off offset:160
	global_load_dwordx4 v[116:119], v[10:11], off offset:192
	global_load_dwordx4 v[120:123], v[10:11], off offset:224
	global_load_dwordx4 v[124:127], v[8:9], off offset:192
	global_load_dwordx4 v[128:131], v[8:9], off offset:224
	v_or_b32_e32 v2, s26, v5
	s_mul_i32 s0, s9, 0x600
	v_add_u32_e32 v8, s0, v2
	v_mov_b32_e32 v9, v0
	v_lshlrev_b64 v[8:9], 2, v[8:9]
	v_lshl_add_u64 v[10:11], s[66:67], 0, v[8:9]
	global_load_dword v4, v[10:11], off
	v_lshl_add_u64 v[10:11], s[70:71], 0, v[8:9]
	v_lshl_add_u64 v[8:9], s[72:73], 0, v[8:9]
	global_load_dword v20, v[10:11], off
	global_load_dword v14, v[8:9], off
	v_mov_b32_e32 v3, v0
	v_mov_b32_e32 v180, 0
	s_cmp_gt_u32 s23, 11
	v_lshlrev_b64 v[8:9], 2, v[2:3]
	s_cbranch_scc0 .LBB0_574
	v_readlane_b32 s8, v248, 47
	v_readlane_b32 s9, v248, 48
	v_readlane_b32 s12, v248, 49
	v_readlane_b32 s13, v248, 50
	v_lshlrev_b32_e32 v140, 2, v2
	s_nop 3
	s_mov_b32 s0, 0
	s_add_u32 s4, s8, s0
	s_addc_u32 s5, s9, 0
	global_load_dword v182, v140, s[4:5]
	s_add_u32 s4, s12, s0
	s_addc_u32 s5, s13, 0
	global_load_dword v183, v140, s[4:5]
	s_cmp_gt_u32 s3, 1
	s_cselect_b32 s0, 0x1800, 0
	s_add_u32 s4, s8, s0
	s_addc_u32 s5, s9, 0
	global_load_dword v184, v140, s[4:5]
	s_add_u32 s4, s12, s0
	s_addc_u32 s5, s13, 0
	global_load_dword v185, v140, s[4:5]
	s_cmp_gt_u32 s3, 2
	s_cselect_b32 s0, 0x3000, 0
	s_add_u32 s4, s8, s0
	s_addc_u32 s5, s9, 0
	global_load_dword v186, v140, s[4:5]
	s_add_u32 s4, s12, s0
	s_addc_u32 s5, s13, 0
	global_load_dword v187, v140, s[4:5]
	s_cmp_gt_u32 s3, 3
	s_cselect_b32 s0, 0x4800, 0
	s_add_u32 s4, s8, s0
	s_addc_u32 s5, s9, 0
	global_load_dword v188, v140, s[4:5]
	s_add_u32 s4, s12, s0
	s_addc_u32 s5, s13, 0
	global_load_dword v189, v140, s[4:5]
	s_cmp_gt_u32 s3, 4
	s_cselect_b32 s0, 0x6000, 0
	s_add_u32 s4, s8, s0
	s_addc_u32 s5, s9, 0
	global_load_dword v190, v140, s[4:5]
	s_add_u32 s4, s12, s0
	s_addc_u32 s5, s13, 0
	global_load_dword v191, v140, s[4:5]
	s_cmp_gt_u32 s3, 5
	s_cselect_b32 s0, 0x7800, 0
	s_add_u32 s4, s8, s0
	s_addc_u32 s5, s9, 0
	global_load_dword v192, v140, s[4:5]
	s_add_u32 s4, s12, s0
	s_addc_u32 s5, s13, 0
	global_load_dword v193, v140, s[4:5]
	s_cmp_gt_u32 s3, 6
	s_cbranch_scc0 .Lci_wait
	s_cmp_gt_u32 s3, 6
	s_cselect_b32 s0, 0x9000, 0
	s_add_u32 s4, s8, s0
	s_addc_u32 s5, s9, 0
	global_load_dword v194, v140, s[4:5]
	s_add_u32 s4, s12, s0
	s_addc_u32 s5, s13, 0
	global_load_dword v195, v140, s[4:5]
	s_cmp_gt_u32 s3, 7
	s_cselect_b32 s0, 0xa800, 0
	s_add_u32 s4, s8, s0
	s_addc_u32 s5, s9, 0
	global_load_dword v196, v140, s[4:5]
	s_add_u32 s4, s12, s0
	s_addc_u32 s5, s13, 0
	global_load_dword v197, v140, s[4:5]
	s_cmp_gt_u32 s3, 8
	s_cselect_b32 s0, 0xc000, 0
	s_add_u32 s4, s8, s0
	s_addc_u32 s5, s9, 0
	global_load_dword v198, v140, s[4:5]
	s_add_u32 s4, s12, s0
	s_addc_u32 s5, s13, 0
	global_load_dword v199, v140, s[4:5]
	s_cmp_gt_u32 s3, 9
	s_cselect_b32 s0, 0xd800, 0
	s_add_u32 s4, s8, s0
	s_addc_u32 s5, s9, 0
	global_load_dword v200, v140, s[4:5]
	s_add_u32 s4, s12, s0
	s_addc_u32 s5, s13, 0
	global_load_dword v201, v140, s[4:5]
	s_cmp_gt_u32 s3, 10
	s_cselect_b32 s0, 0xf000, 0
	s_add_u32 s4, s8, s0
	s_addc_u32 s5, s9, 0
	global_load_dword v202, v140, s[4:5]
	s_add_u32 s4, s12, s0
	s_addc_u32 s5, s13, 0
	global_load_dword v203, v140, s[4:5]
	s_cmp_gt_u32 s3, 11
	s_cselect_b32 s0, 0x10800, 0
	s_add_u32 s4, s8, s0
	s_addc_u32 s5, s9, 0
	global_load_dword v204, v140, s[4:5]
	s_add_u32 s4, s12, s0
	s_addc_u32 s5, s13, 0
	global_load_dword v205, v140, s[4:5]
	s_cmp_gt_u32 s3, 12
	s_cbranch_scc0 .Lci_wait
	s_cmp_gt_u32 s3, 12
	s_cselect_b32 s0, 0x12000, 0
	s_add_u32 s4, s8, s0
	s_addc_u32 s5, s9, 0
	global_load_dword v206, v140, s[4:5]
	s_add_u32 s4, s12, s0
	s_addc_u32 s5, s13, 0
	global_load_dword v207, v140, s[4:5]
	s_cmp_gt_u32 s3, 13
	s_cselect_b32 s0, 0x13800, 0
	s_add_u32 s4, s8, s0
	s_addc_u32 s5, s9, 0
	global_load_dword v208, v140, s[4:5]
	s_add_u32 s4, s12, s0
	s_addc_u32 s5, s13, 0
	global_load_dword v209, v140, s[4:5]
	s_cmp_gt_u32 s3, 14
	s_cselect_b32 s0, 0x15000, 0
	s_add_u32 s4, s8, s0
	s_addc_u32 s5, s9, 0
	global_load_dword v132, v140, s[4:5]
	s_add_u32 s4, s12, s0
	s_addc_u32 s5, s13, 0
	global_load_dword v133, v140, s[4:5]
	s_cmp_gt_u32 s3, 15
	s_cselect_b32 s0, 0x16800, 0
	s_add_u32 s4, s8, s0
	s_addc_u32 s5, s9, 0
	global_load_dword v134, v140, s[4:5]
	s_add_u32 s4, s12, s0
	s_addc_u32 s5, s13, 0
	global_load_dword v135, v140, s[4:5]
	s_cmp_gt_u32 s3, 16
	s_cselect_b32 s0, 0x18000, 0
	s_add_u32 s4, s8, s0
	s_addc_u32 s5, s9, 0
	global_load_dword v136, v140, s[4:5]
	s_add_u32 s4, s12, s0
	s_addc_u32 s5, s13, 0
	global_load_dword v137, v140, s[4:5]
	s_cmp_gt_u32 s3, 17
	s_cselect_b32 s0, 0x19800, 0
	s_add_u32 s4, s8, s0
	s_addc_u32 s5, s9, 0
	global_load_dword v138, v140, s[4:5]
	s_add_u32 s4, s12, s0
	s_addc_u32 s5, s13, 0
	global_load_dword v139, v140, s[4:5]
.Lci_wait:
	s_waitcnt vmcnt(0)
	v_fma_f32 v180, v180, v182, v183
	s_cmp_gt_u32 s3, 1
	s_cbranch_scc0 .Lci_done
	v_fma_f32 v180, v180, v184, v185
	s_cmp_gt_u32 s3, 2
	s_cbranch_scc0 .Lci_done
	v_fma_f32 v180, v180, v186, v187
	s_cmp_gt_u32 s3, 3
	s_cbranch_scc0 .Lci_done
	v_fma_f32 v180, v180, v188, v189
	s_cmp_gt_u32 s3, 4
	s_cbranch_scc0 .Lci_done
	v_fma_f32 v180, v180, v190, v191
	s_cmp_gt_u32 s3, 5
	s_cbranch_scc0 .Lci_done
	v_fma_f32 v180, v180, v192, v193
	s_cmp_gt_u32 s3, 6
	s_cbranch_scc0 .Lci_done
	v_fma_f32 v180, v180, v194, v195
	s_cmp_gt_u32 s3, 7
	s_cbranch_scc0 .Lci_done
	v_fma_f32 v180, v180, v196, v197
	s_cmp_gt_u32 s3, 8
	s_cbranch_scc0 .Lci_done
	v_fma_f32 v180, v180, v198, v199
	s_cmp_gt_u32 s3, 9
	s_cbranch_scc0 .Lci_done
	v_fma_f32 v180, v180, v200, v201
	s_cmp_gt_u32 s3, 10
	s_cbranch_scc0 .Lci_done
	v_fma_f32 v180, v180, v202, v203
	s_cmp_gt_u32 s3, 11
	s_cbranch_scc0 .Lci_done
	v_fma_f32 v180, v180, v204, v205
	s_cmp_gt_u32 s3, 12
	s_cbranch_scc0 .Lci_done
	v_fma_f32 v180, v180, v206, v207
	s_cmp_gt_u32 s3, 13
	s_cbranch_scc0 .Lci_done
	v_fma_f32 v180, v180, v208, v209
	s_cmp_gt_u32 s3, 14
	s_cbranch_scc0 .Lci_done
	v_fma_f32 v180, v180, v132, v133
	s_cmp_gt_u32 s3, 15
	s_cbranch_scc0 .Lci_done
	v_fma_f32 v180, v180, v134, v135
	s_cmp_gt_u32 s3, 16
	s_cbranch_scc0 .Lci_done
	v_fma_f32 v180, v180, v136, v137
	s_cmp_gt_u32 s3, 17
	s_cbranch_scc0 .Lci_done
	v_fma_f32 v180, v180, v138, v139
.Lci_done:
.LBB0_574:
	v_and_b32_e32 v15, 15, v6
	v_ashrrev_i32_e32 v16, 4, v6
	v_lshlrev_b32_e32 v17, 3, v15
	s_mul_i32 s8, s3, 0x1c0
	v_or_b32_e32 v1, s26, v17
	v_lshlrev_b32_e32 v37, 1, v16
	v_mov_b32_e32 v2, v0
	v_mov_b32_e32 v3, v0
	v_add3_u32 v8, s8, -3, v37
	v_lshlrev_b32_e32 v6, 1, v1
	v_mov_b32_e32 v7, v0
	v_mov_b32_e32 v1, v0
	s_waitcnt vmcnt(19)
	v_mov_b64_e32 v[134:135], v[2:3]
	v_lshl_add_u64 v[160:161], s[16:17], 0, v[6:7]
	v_cmp_lt_i32_e32 vcc, -1, v8
	v_mov_b64_e32 v[132:133], v[0:1]
	s_and_saveexec_b64 s[0:1], vcc
	s_cbranch_execz .LBB0_576
	v_mov_b32_e32 v9, v0
	v_lshlrev_b64 v[10:11], 13, v[8:9]
	v_lshl_add_u64 v[10:11], v[160:161], 0, v[10:11]
	global_load_dwordx4 v[132:135], v[10:11], off

.LBB0_601:
	s_and_b64 vcc, exec, s[6:7]
	s_cbranch_vccz .LBB0_510
	s_branch .LBB0_510
.LBB0_605:
	v_readlane_b32 s0, v246, 0
	s_cmp_eq_u32 s0, 0
	v_readlane_b32 s0, v248, 59
	s_cselect_b64 s[6:7], -1, 0
	v_readlane_b32 s1, v248, 60
	s_and_b64 s[0:1], s[6:7], s[0:1]
	s_and_b64 vcc, exec, s[0:1]
	v_readlane_b32 s0, v247, 0
	v_readlane_b32 s1, v247, 1
	v_readlane_b32 s94, v246, 7
	v_readlane_b32 s82, v249, 8
	v_cndmask_b32_e64 v1, 0, 1, s[0:1]
	v_readlane_b32 s0, v246, 5
	v_readlane_b32 s84, v249, 10
	v_cmp_ne_u32_e64 s[36:37], 1, v1
	s_mov_b32 s90, s0
	v_readlane_b32 s95, v246, 8
	v_readlane_b32 s83, v249, 9
	v_readlane_b32 s85, v249, 11
	v_readlane_b32 s1, v246, 6
	s_cbranch_vccz .LBB0_652
	v_mov_b32_e32 v39, v181
	v_mov_b32_e32 v30, 1.0
	v_ashrrev_i32_e32 v34, 5, v39
	s_and_b64 vcc, exec, s[36:37]
	v_ashrrev_i32_e32 v35, 31, v34
	v_mov_b32_e32 v32, 1.0
	s_cbranch_vccnz .LBB0_608
	v_readlane_b32 s44, v249, 12
	v_readlane_b32 s45, v249, 13
	v_readlane_b32 s46, v249, 14
	v_readlane_b32 s47, v249, 15
	v_lshl_add_u64 v[2:3], v[34:35], 2, s[44:45]
	global_load_dword v32, v[2:3], off offset:1024
	v_readlane_b32 s48, v249, 16
	v_readlane_b32 s49, v249, 17
	v_readlane_b32 s50, v249, 18
	v_readlane_b32 s51, v249, 19

.LBB0_670:
	v_add_u32_e32 v30, 0x70, v30
	v_ashrrev_i32_e32 v33, 31, v30
	v_mad_u64_u32 v[30:31], s[0:1], v30, s21, 0
	v_mov_b32_e32 v32, v31
	v_mad_u64_u32 v[32:33], s[0:1], v33, s21, v[32:33]
	v_mov_b32_e32 v31, v32
	v_lshl_add_u64 v[30:31], v[30:31], 2, s[38:39]
	v_lshl_add_u64 v[30:31], v[30:31], 0, s[26:27]
	v_lshl_add_u64 v[30:31], v[30:31], 0, v[34:35]
	global_load_dwordx4 v[30:33], v[30:31], off nt
.LBB0_671:
	s_lshr_b32 s0, s28, 7
	v_cvt_f32_u32_e32 v35, s0
	ds_read2st64_b32 v[42:43], v45 offset1:2
	s_sub_i32 s9, 0, s0
	s_abs_i32 s8, s23
	v_rcp_iflag_f32_e32 v35, v35
	s_ashr_i32 s1, s23, 31
	s_waitcnt lgkmcnt(0)
	v_cvt_pk_bf16_f32 v64, v42, v43
	ds_read2st64_b32 v[42:43], v45 offset0:4 offset1:6
	v_mul_f32_e32 v35, 0x4f7ffffe, v35
	v_cvt_u32_f32_e32 v35, v35
	v_mov_b32_e32 v37, v0
	s_mov_b32 s28, s21
	s_waitcnt lgkmcnt(0)
	v_cvt_pk_bf16_f32 v65, v42, v43
	v_readfirstlane_b32 s12, v35
	s_mul_i32 s9, s9, s12
	s_mul_hi_u32 s9, s12, s9
	s_add_i32 s12, s12, s9
	s_mul_hi_u32 s9, s8, s12
	s_mul_i32 s12, s9, s0
	s_sub_i32 s8, s8, s12
	s_add_i32 s12, s9, 1
	s_sub_i32 s13, s8, s0
	s_cmp_ge_u32 s8, s0
	ds_read2st64_b32 v[42:43], v45 offset0:8 offset1:10
	s_cselect_b32 s9, s12, s9
	s_cselect_b32 s8, s13, s8
	s_add_i32 s12, s9, 1
	s_cmp_ge_u32 s8, s0
	s_cselect_b32 s8, s12, s9
	s_xor_b32 s8, s8, s1
	s_waitcnt lgkmcnt(0)
	v_cvt_pk_bf16_f32 v66, v42, v43
	ds_read2st64_b32 v[42:43], v45 offset0:12 offset1:14
	s_sub_i32 s1, s8, s1
	s_mul_i32 s0, s1, s0
	s_sub_i32 s0, s23, s0
	s_lshl_b32 s8, s0, 7
	s_lshl_b32 s0, s1, 8
	s_add_u32 s0, s36, s0
	s_waitcnt lgkmcnt(0)
	v_cvt_pk_bf16_f32 v67, v42, v43
	v_add_u32_e32 v42, s8, v41
	s_addc_u32 s1, s37, 0
	v_ashrrev_i32_e32 v43, 31, v42
	v_lshl_add_u64 v[38:39], s[0:1], 0, v[36:37]
	v_lshlrev_b64 v[42:43], 12, v[42:43]
	v_lshl_add_u64 v[42:43], v[38:39], 0, v[42:43]
	global_store_dwordx4 v[42:43], v[64:67], off
	ds_read2st64_b32 v[42:43], v59 offset1:2
	s_add_i32 s3, s3, 28
	s_add_i32 s4, s4, 28
	s_cmpk_lt_i32 s22, 0x964
	s_mov_b64 s[36:37], s[24:25]
	s_waitcnt lgkmcnt(0)
	v_cvt_pk_bf16_f32 v64, v42, v43
	ds_read2st64_b32 v[42:43], v59 offset0:4 offset1:6
	s_mov_b32 s23, s5
	s_waitcnt lgkmcnt(0)
	v_cvt_pk_bf16_f32 v65, v42, v43
	ds_read2st64_b32 v[42:43], v59 offset0:8 offset1:10
	s_waitcnt lgkmcnt(0)
	v_cvt_pk_bf16_f32 v66, v42, v43
	ds_read2st64_b32 v[42:43], v59 offset0:12 offset1:14
	s_waitcnt lgkmcnt(0)
	v_cvt_pk_bf16_f32 v67, v42, v43
	v_add_u32_e32 v42, s8, v58
	v_ashrrev_i32_e32 v43, 31, v42
	v_lshlrev_b64 v[42:43], 12, v[42:43]
	v_lshl_add_u64 v[42:43], v[38:39], 0, v[42:43]
	global_store_dwordx4 v[42:43], v[64:67], off
	ds_read2st64_b32 v[42:43], v61 offset1:2
	s_waitcnt lgkmcnt(0)
	v_cvt_pk_bf16_f32 v64, v42, v43
	ds_read2st64_b32 v[42:43], v61 offset0:4 offset1:6
	s_waitcnt lgkmcnt(0)
	v_cvt_pk_bf16_f32 v65, v42, v43
	ds_read2st64_b32 v[42:43], v61 offset0:8 offset1:10
	s_waitcnt lgkmcnt(0)
	v_cvt_pk_bf16_f32 v66, v42, v43
	ds_read2st64_b32 v[42:43], v61 offset0:12 offset1:14
	s_waitcnt lgkmcnt(0)
	v_cvt_pk_bf16_f32 v67, v42, v43
	v_add_u32_e32 v42, s8, v60
	v_ashrrev_i32_e32 v43, 31, v42
	v_lshlrev_b64 v[42:43], 12, v[42:43]
	v_lshl_add_u64 v[42:43], v[38:39], 0, v[42:43]
	global_store_dwordx4 v[42:43], v[64:67], off
	ds_read2st64_b32 v[42:43], v63 offset1:2
	s_waitcnt lgkmcnt(0)
	v_cvt_pk_bf16_f32 v64, v42, v43
	ds_read2st64_b32 v[42:43], v63 offset0:4 offset1:6
	s_waitcnt lgkmcnt(0)
	v_cvt_pk_bf16_f32 v65, v42, v43
	ds_read2st64_b32 v[42:43], v63 offset0:8 offset1:10
	s_waitcnt lgkmcnt(0)
	v_cvt_pk_bf16_f32 v66, v42, v43
	ds_read2st64_b32 v[42:43], v63 offset0:12 offset1:14
	s_waitcnt lgkmcnt(0)
	v_cvt_pk_bf16_f32 v67, v42, v43
	v_add_u32_e32 v42, s8, v62
	v_ashrrev_i32_e32 v43, 31, v42
	v_lshlrev_b64 v[42:43], 12, v[42:43]
	v_lshl_add_u64 v[38:39], v[38:39], 0, v[42:43]
	global_store_dwordx4 v[38:39], v[64:67], off
	s_waitcnt lgkmcnt(0)
	s_barrier
	s_cbranch_scc0 .LBB0_702
	s_waitcnt vmcnt(4)
	v_pk_mul_f32 v[8:9], v[8:9], v[68:69] op_sel_hi:[1,0]
	v_pk_mul_f32 v[6:7], v[6:7], v[68:69] op_sel_hi:[1,0]
	v_pk_mul_f32 v[4:5], v[4:5], v[40:41] op_sel_hi:[1,0]
	v_pk_mul_f32 v[2:3], v[2:3], v[40:41] op_sel_hi:[1,0]
	v_pk_mul_f32 v[12:13], v[12:13], v[46:47] op_sel_hi:[1,0]
	v_pk_mul_f32 v[10:11], v[10:11], v[46:47] op_sel_hi:[1,0]
	v_pk_mul_f32 v[16:17], v[16:17], v[44:45] op_sel_hi:[1,0]
	v_pk_mul_f32 v[14:15], v[14:15], v[44:45] op_sel_hi:[1,0]
	v_pk_mul_f32 v[20:21], v[20:21], v[50:51] op_sel_hi:[1,0]
	v_pk_mul_f32 v[18:19], v[18:19], v[50:51] op_sel_hi:[1,0]
	v_pk_mul_f32 v[24:25], v[24:25], v[48:49] op_sel_hi:[1,0]
	v_pk_mul_f32 v[22:23], v[22:23], v[48:49] op_sel_hi:[1,0]
	v_pk_mul_f32 v[28:29], v[28:29], v[52:53] op_sel_hi:[1,0]
	v_pk_mul_f32 v[26:27], v[26:27], v[52:53] op_sel_hi:[1,0]
	v_pk_mul_f32 v[32:33], v[32:33], v[70:71] op_sel_hi:[1,0]
	v_pk_mul_f32 v[30:31], v[30:31], v[70:71] op_sel_hi:[1,0]

.LBB0_686:
	s_lshr_b32 s26, s21, 7
	v_cvt_f32_u32_e32 v2, s26
	s_and_b32 s8, s5, 0xffff
	v_cvt_f32_u32_e32 v3, s8
	v_mov_b32_e32 v68, 1.0
	v_rcp_iflag_f32_e32 v4, v2
	v_mov_b32_e32 v40, 1.0
	v_mul_f32_e32 v4, v3, v4
	v_trunc_f32_e32 v4, v4
	v_cvt_u32_f32_e32 v5, v4
	v_fma_f32 v3, -v4, v2, v3
	v_cmp_ge_f32_e64 s[8:9], |v3|, v2
	s_cmp_lg_u64 s[8:9], 0
	v_readfirstlane_b32 s8, v5
	s_addc_u32 s29, s8, 0
	s_and_b32 s8, s29, 0xffff
	v_lshl_add_u32 v30, s8, 7, v1
	s_cmp_lg_u64 s[0:1], 0
	v_ashrrev_i32_e32 v31, 31, v30
	s_cselect_b64 s[8:9], -1, 0
	s_cmp_eq_u64 s[0:1], 0
	v_lshl_add_u64 v[42:43], v[30:31], 2, s[0:1]
	s_cbranch_scc1 .LBB0_688
	global_load_dword v40, v[42:43], off
.LBB0_688:
	v_mad_u64_u32 v[2:3], s[0:1], v30, s21, 0
	s_mul_i32 s29, s29, s26
	v_mov_b32_e32 v4, v3
	s_sub_i32 s29, s5, s29
	v_mad_u64_u32 v[4:5], s[0:1], v31, s21, v[4:5]
	v_mov_b32_e32 v3, v4
	s_lshl_b32 s0, s29, 9
	v_lshl_add_u64 v[2:3], v[2:3], 2, s[38:39]
	s_and_b32 s26, s0, 0x3fe00
	v_lshl_add_u64 v[2:3], v[2:3], 0, s[26:27]
	v_mov_b32_e32 v35, v0
	v_lshl_add_u64 v[2:3], v[2:3], 0, v[34:35]
	global_load_dwordx4 v[2:5], v[2:3], off nt
	v_cndmask_b32_e64 v6, 0, 1, s[8:9]
	v_cmp_ne_u32_e64 s[0:1], 1, v6
	s_andn2_b64 vcc, exec, s[8:9]
	s_cbranch_vccnz .LBB0_690
	global_load_dword v68, v[42:43], off offset:64

.LBB0_698:
	v_add_u32_e32 v22, 0x50, v30
	v_ashrrev_i32_e32 v25, 31, v22
	v_mad_u64_u32 v[22:23], s[8:9], v22, s21, 0
	v_mov_b32_e32 v24, v23
	v_mad_u64_u32 v[24:25], s[8:9], v25, s21, v[24:25]
	v_mov_b32_e32 v23, v24
	v_lshl_add_u64 v[22:23], v[22:23], 2, s[38:39]
	v_lshl_add_u64 v[22:23], v[22:23], 0, s[26:27]
	v_lshl_add_u64 v[22:23], v[22:23], 0, v[34:35]
	global_load_dwordx4 v[22:25], v[22:23], off nt
	v_mov_b32_e32 v70, 1.0
	s_and_b64 vcc, exec, s[0:1]
	v_mov_b32_e32 v52, 1.0
	s_cbranch_vccnz .LBB0_700
	global_load_dword v52, v[42:43], off offset:384
.LBB0_700:
	v_add_u32_e32 v26, 0x60, v30
	v_ashrrev_i32_e32 v29, 31, v26
	v_mad_u64_u32 v[26:27], s[8:9], v26, s21, 0
	v_mov_b32_e32 v28, v27
	v_mad_u64_u32 v[28:29], s[8:9], v29, s21, v[28:29]
	v_mov_b32_e32 v27, v28
	v_lshl_add_u64 v[26:27], v[26:27], 2, s[38:39]
	v_lshl_add_u64 v[26:27], v[26:27], 0, s[26:27]
	v_mov_b32_e32 v35, v0
	v_lshl_add_u64 v[26:27], v[26:27], 0, v[34:35]
	global_load_dwordx4 v[26:29], v[26:27], off nt
	s_and_b64 vcc, exec, s[0:1]
	s_cbranch_vccnz .LBB0_670
	global_load_dword v70, v[42:43], off offset:448
	s_branch .LBB0_670
